# ssd_sample conv loop: 12 loads of an iteration in flight (was 4 serialized round trips)
# speedup vs baseline: 1.0117x; 1.0022x over previous
.LBB0_292:
	s_or_b64 exec, exec, s[24:25]
	v_ashrrev_i32_e32 v3, 31, v2
	v_lshlrev_b64 v[10:11], 2, v[2:3]
	v_lshl_add_u64 v[12:13], s[20:21], 0, v[10:11]
	v_add_co_u32_e32 v14, vcc, 0x1000, v12
	global_load_dword v9, v[12:13], off
	s_nop 0
	v_addc_co_u32_e32 v15, vcc, 0, v13, vcc
	global_load_dword v14, v[14:15], off offset:2048
	v_add_co_u32_e32 v12, vcc, 0x3000, v12
	v_lshlrev_b64 v[2:3], 1, v[2:3]
	s_nop 0
	v_addc_co_u32_e32 v13, vcc, 0, v13, vcc
	global_load_dword v15, v[12:13], off
	v_lshl_add_u64 v[12:13], s[12:13], 0, v[2:3]
	global_load_ushort v244, v[12:13], off
	v_readlane_b32 s36, v242, 2
	v_readlane_b32 s40, v242, 6
	v_readlane_b32 s41, v242, 7
	s_movk_i32 s24, 0x1000
	v_readlane_b32 s42, v242, 8
	v_readlane_b32 s43, v242, 9
	v_readlane_b32 s37, v242, 3
	v_readlane_b32 s38, v242, 4
	v_readlane_b32 s39, v242, 5
	v_readlane_b32 s44, v242, 10
	v_readlane_b32 s45, v242, 11
	v_readlane_b32 s46, v242, 12
	v_readlane_b32 s47, v242, 13
	v_readlane_b32 s48, v242, 14
	v_readlane_b32 s49, v242, 15
	v_readlane_b32 s50, v242, 16
	v_readlane_b32 s51, v242, 17
	v_lshl_add_u64 v[12:13], s[14:15], 0, v[2:3]
	global_load_ushort v245, v[12:13], off
	v_lshl_add_u64 v[12:13], s[16:17], 0, v[2:3]
	v_lshl_add_u64 v[2:3], s[18:19], 0, v[2:3]
	global_load_ushort v246, v[12:13], off
	s_nop 0
	global_load_ushort v247, v[2:3], off
	v_lshl_add_u64 v[2:3], s[40:41], 0, v[10:11]
	v_add_co_u32_e32 v12, vcc, s24, v2
	s_movk_i32 s24, 0x3000
	s_nop 0
	v_addc_co_u32_e32 v13, vcc, 0, v3, vcc
	global_load_dword v22, v[12:13], off offset:2048
	v_add_co_u32_e32 v12, vcc, s24, v2
	s_movk_i32 s24, 0x4000
	s_nop 0
	v_addc_co_u32_e32 v13, vcc, 0, v3, vcc
	global_load_dword v21, v[2:3], off
	s_nop 0
	global_load_dword v12, v[12:13], off
	v_add_co_u32_e32 v2, vcc, s24, v2
	s_movk_i32 s24, 0xff
	s_nop 0
	v_addc_co_u32_e32 v3, vcc, 0, v3, vcc
	global_load_dword v13, v[2:3], off offset:2048
	v_lshl_add_u64 v[2:3], s[42:43], 0, v[10:11]
	global_load_dword v2, v[2:3], off
	v_lshl_add_u32 v3, v6, 2, v8
	v_cmp_lt_i32_e32 vcc, s24, v5
	s_or_b64 s[22:23], vcc, s[22:23]
	s_waitcnt vmcnt(0)
	v_lshlrev_b32_e32 v16, 16, v244
	v_lshlrev_b32_e32 v17, 16, v245
	v_lshlrev_b32_e32 v18, 16, v246
	v_lshlrev_b32_e32 v19, 16, v247
	v_fma_f32 v6, v9, v21, v2
	v_fmac_f32_e32 v6, v14, v22
	v_fmac_f32_e32 v6, v15, v12
	v_fmac_f32_e32 v6, v13, v16
	v_mul_f32_e32 v8, 0xbfb8aa3b, v6
	v_exp_f32_e32 v8, v8
	s_nop 0
	v_add_f32_e32 v8, 1.0, v8
	v_rcp_f32_e32 v8, v8
	s_nop 0
	v_mul_f32_e32 v6, v6, v8
	ds_write_b32 v3, v6
	v_fma_f32 v6, v14, v21, v2
	v_fmac_f32_e32 v6, v15, v22
	v_fmac_f32_e32 v6, v12, v16
	v_fmac_f32_e32 v6, v13, v17
	v_mul_f32_e32 v8, 0xbfb8aa3b, v6
	v_exp_f32_e32 v8, v8
	s_nop 0
	v_add_f32_e32 v8, 1.0, v8
	v_rcp_f32_e32 v8, v8
	s_nop 0
	v_mul_f32_e32 v6, v6, v8
	v_lshl_add_u32 v8, v7, 2, v3
	ds_write_b32 v8, v6
	v_fma_f32 v6, v15, v21, v2
	v_fmac_f32_e32 v6, v22, v16
	v_fmac_f32_e32 v6, v12, v17
	v_fmac_f32_e32 v6, v13, v18
	v_mul_f32_e32 v8, 0xbfb8aa3b, v6
	v_exp_f32_e32 v8, v8
	v_fmac_f32_e32 v2, v21, v16
	v_fmac_f32_e32 v2, v22, v17
	v_fmac_f32_e32 v2, v12, v18
	v_add_f32_e32 v8, 1.0, v8
	v_rcp_f32_e32 v8, v8
	v_fmac_f32_e32 v2, v13, v19
	v_mul_f32_e32 v6, v6, v8
	v_lshl_add_u32 v8, v7, 3, v3
	ds_write_b32 v8, v6
	v_mul_f32_e32 v6, 0xbfb8aa3b, v2
	v_exp_f32_e32 v6, v6
	v_mad_u32_u24 v3, v7, 12, v3
	v_add_f32_e32 v6, 1.0, v6
	v_rcp_f32_e32 v6, v6
	s_nop 0
	v_mul_f32_e32 v2, v2, v6
	ds_write_b32 v3, v2
	v_add_u32_e32 v2, 0x200, v5
	v_mov_b32_e32 v5, v2
	s_andn2_b64 exec, exec, s[22:23]
	s_cbranch_execz .LBB0_301
